# attention: per-workgroup partial-numerator scratch re-laid out lane-major (coalesced dwordx4 stores, 16-byte gathers in the final pass); final-pass epilogue loads issued up front; scan false-dependenc
# speedup vs baseline: 1.0038x; 1.0020x over previous
; __device__ __forceinline__ unsigned cvt_pk_bf16(float lo, float hi) { unsigned r; asm volatile("v_cvt_pk_bf16_f32 %0, %1, %2" : "=v"(r) : "v"(lo), "v"(hi)); return r; }
; __device__ __forceinline__ float bflo(unsigned w) { return __uint_as_float(w << 16); }
; __device__ __forceinline__ float bfhi(unsigned w) { return __uint_as_float(w & 0xffff0000u); }
; template <bool DRY>
; __device__ __forceinline__ void attn_unit(const Args& a, LAS unsigned char* lds, int cidx, int h, int lane, int wave) {
;     ...
; #pragma unroll
;             for (int gq = 0; gq < 2; ++gq) {
;                 const int qi = qpos[gq] - Pu;
;                 const float dt = den[gq] + *(const float*)((const char*)Xd + (unsigned)qi * 4u) + *(const float*)((const char*)Xd + (unsigned)(512 + qi) * 4u);
;                 const float inv = 1.0f / dt;
;                 const unsigned x1o = ((unsigned)qi * 128 + 4 * fq) * 2u, x4o = ((unsigned)(512 + qi) * 128 + 4 * fq) * 2u;
;                 const unsigned go = ((unsigned)(seq_start + qpos[gq]) * AW + h * 128 + 4 * fq) * 2u;
; #pragma unroll
;                 for (int c = 0; c < 8; ++c) {
;                     bf16_t* gp = (bf16_t*)((char*)GA + go) - 16 * c + 16 * c;
;                     const u32x2 xa = *(const u32x2*)((const char*)X + x1o + 32 * c), xb = *(const u32x2*)((const char*)X + x4o + 32 * c);
;                     const f32x4 t = o[gq][c] + (f32x4){bflo(xa.x), bfhi(xa.x), bflo(xa.y), bfhi(xa.y)} + (f32x4){bflo(xb.x), bfhi(xb.x), bflo(xb.y), bfhi(xb.y)};
;                     const u32x2 gg = *(const u32x2*)(gp + 16 * c);
;                     u32x2 w; w.x = cvt_pk_bf16(t[0] * inv * bflo(gg.x), t[1] * inv * bfhi(gg.x)); w.y = cvt_pk_bf16(t[2] * inv * bflo(gg.y), t[3] * inv * bfhi(gg.y));
;                     if (!DRY || inv == 1.2345e33f) *(u32x2*)(gp + 16 * c) = w;
;                 }
.LBB0_606:
	v_lshlrev_b32_e32 v95, 5, v166
	v_subrev_u32_e32 v76, s50, v190
	v_add_u32_e32 v66, v192, v187
	v_lshlrev_b32_e32 v72, 2, v76
	v_add_u32_e32 v73, 0x800, v72
	v_lshrrev_b32_e32 v94, 4, v76
	v_and_b32_e32 v68, 15, v76
	v_lshlrev_b32_e32 v68, 4, v68
	v_lshl_add_u32 v68, v94, 12, v68
	v_add_u32_e32 v68, v68, v95
	v_and_b32_e32 v94, 3, v76
	v_lshlrev_b32_e32 v94, 3, v94
	v_lshrrev_b32_e32 v69, 6, v76
	v_add_u32_e32 v94, v94, v69
	v_bfe_u32 v69, v76, 2, 4
	v_lshlrev_b32_e32 v69, 4, v69
	v_lshl_add_u32 v69, v94, 12, v69
	v_add_u32_e32 v69, v69, v95
	v_add_u32_e32 v69, 0x20000, v69
	v_subrev_u32_e32 v77, s50, v189
	v_add_u32_e32 v67, v191, v187
	v_lshlrev_b32_e32 v74, 2, v77
	v_add_u32_e32 v75, 0x800, v74
	v_lshrrev_b32_e32 v94, 4, v77
	v_and_b32_e32 v70, 15, v77
	v_lshlrev_b32_e32 v70, 4, v70
	v_lshl_add_u32 v70, v94, 12, v70
	v_add_u32_e32 v70, v70, v95
	v_and_b32_e32 v94, 3, v77
	v_lshlrev_b32_e32 v94, 3, v94
	v_lshrrev_b32_e32 v71, 6, v77
	v_add_u32_e32 v94, v94, v71
	v_bfe_u32 v71, v77, 2, 4
	v_lshlrev_b32_e32 v71, 4, v71
	v_lshl_add_u32 v71, v94, 12, v71
	v_add_u32_e32 v71, v71, v95
	v_add_u32_e32 v71, 0x20000, v71
	global_load_dword v78, v72, s[30:31]
	global_load_dword v79, v73, s[30:31]
	global_load_dword v80, v74, s[30:31]
	global_load_dword v81, v75, s[30:31]
	global_load_dwordx2 v[194:195], v66, s[20:21]
	global_load_dwordx2 v[196:197], v66, s[20:21] offset:32
	global_load_dwordx4 v[96:99], v68, s[22:23]
	global_load_dwordx4 v[100:103], v69, s[22:23]
	global_load_dwordx2 v[198:199], v66, s[20:21] offset:64
	global_load_dwordx2 v[200:201], v66, s[20:21] offset:96
	global_load_dwordx4 v[104:107], v68, s[22:23] offset:1024
	global_load_dwordx4 v[108:111], v69, s[22:23] offset:1024
	global_load_dwordx2 v[202:203], v66, s[20:21] offset:128
	global_load_dwordx2 v[204:205], v66, s[20:21] offset:160
	global_load_dwordx4 v[112:115], v68, s[22:23] offset:2048
	global_load_dwordx4 v[116:119], v69, s[22:23] offset:2048
	global_load_dwordx2 v[206:207], v66, s[20:21] offset:192
	global_load_dwordx2 v[208:209], v66, s[20:21] offset:224
	global_load_dwordx4 v[120:123], v68, s[22:23] offset:3072
	global_load_dwordx4 v[124:127], v69, s[22:23] offset:3072
	global_load_dwordx2 v[210:211], v67, s[20:21]
	global_load_dwordx2 v[212:213], v67, s[20:21] offset:32
	global_load_dwordx4 v[128:131], v70, s[22:23]
	global_load_dwordx4 v[132:135], v71, s[22:23]
	global_load_dwordx2 v[214:215], v67, s[20:21] offset:64
	global_load_dwordx2 v[216:217], v67, s[20:21] offset:96
	global_load_dwordx4 v[136:139], v70, s[22:23] offset:1024
	global_load_dwordx4 v[140:143], v71, s[22:23] offset:1024
	global_load_dwordx2 v[218:219], v67, s[20:21] offset:128
	global_load_dwordx2 v[220:221], v67, s[20:21] offset:160
	global_load_dwordx4 v[144:147], v70, s[22:23] offset:2048
	global_load_dwordx4 v[148:151], v71, s[22:23] offset:2048
	global_load_dwordx2 v[222:223], v67, s[20:21] offset:192
	global_load_dwordx2 v[224:225], v67, s[20:21] offset:224
	global_load_dwordx4 v[152:155], v70, s[22:23] offset:3072
	global_load_dwordx4 v[156:159], v71, s[22:23] offset:3072
	s_waitcnt vmcnt(34)
	v_add_f32_e32 v92, v65, v78
	v_add_f32_e32 v92, v92, v79
	s_waitcnt vmcnt(32)
	v_add_f32_e32 v93, v64, v80
	v_add_f32_e32 v93, v93, v81
	v_div_scale_f32 v84, s[6:7], v92, v92, 1.0
	v_rcp_f32_e32 v85, v84
	v_div_scale_f32 v86, vcc, 1.0, v92, 1.0
	v_fma_f32 v87, -v84, v85, 1.0
	v_fmac_f32_e32 v85, v87, v85
	v_mul_f32_e32 v87, v86, v85
	v_fma_f32 v88, -v84, v87, v86
	v_fmac_f32_e32 v87, v88, v85
	v_fma_f32 v88, -v84, v87, v86
	v_div_fmas_f32 v87, v88, v85, v87
	v_div_fixup_f32 v82, v87, v92, 1.0
	v_div_scale_f32 v84, s[6:7], v93, v93, 1.0
	v_rcp_f32_e32 v85, v84
	v_div_scale_f32 v86, vcc, 1.0, v93, 1.0
	v_fma_f32 v87, -v84, v85, 1.0
	v_fmac_f32_e32 v85, v87, v85
	v_mul_f32_e32 v87, v86, v85
	v_fma_f32 v88, -v84, v87, v86
	v_fmac_f32_e32 v87, v88, v85
	v_fma_f32 v88, -v84, v87, v86
	v_div_fmas_f32 v87, v88, v85, v87
	v_div_fixup_f32 v83, v87, v93, 1.0
	s_waitcnt vmcnt(28)
	v_lshlrev_b32_e32 v84, 16, v96
	v_and_b32_e32 v85, 0xffff0000, v96
	v_lshlrev_b32_e32 v86, 16, v97
	v_and_b32_e32 v87, 0xffff0000, v97
	v_lshlrev_b32_e32 v88, 16, v100
	v_and_b32_e32 v89, 0xffff0000, v100
	v_lshlrev_b32_e32 v90, 16, v101
	v_and_b32_e32 v91, 0xffff0000, v101
	v_pk_add_f32 v[84:85], v[60:61], v[84:85]
	v_pk_add_f32 v[86:87], v[62:63], v[86:87]
	v_pk_add_f32 v[84:85], v[84:85], v[88:89]
	v_pk_add_f32 v[86:87], v[86:87], v[90:91]
	v_mul_f32_e32 v84, v82, v84
	v_mul_f32_e32 v85, v82, v85
	v_mul_f32_e32 v86, v82, v86
	v_mul_f32_e32 v87, v82, v87
	v_lshlrev_b32_e32 v88, 16, v194
	v_and_b32_e32 v89, 0xffff0000, v194
	v_lshlrev_b32_e32 v90, 16, v195
	v_and_b32_e32 v91, 0xffff0000, v195
	v_mul_f32_e32 v84, v84, v88
	v_mul_f32_e32 v85, v85, v89
	v_mul_f32_e32 v86, v86, v90
	v_mul_f32_e32 v87, v87, v91
	v_cvt_pk_bf16_f32 v84, v84, v85
	v_cvt_pk_bf16_f32 v85, v86, v87
	global_store_dwordx2 v66, v[84:85], s[20:21]
	s_waitcnt vmcnt(29)
	v_lshlrev_b32_e32 v84, 16, v98
	v_and_b32_e32 v85, 0xffff0000, v98
	v_lshlrev_b32_e32 v86, 16, v99
	v_and_b32_e32 v87, 0xffff0000, v99
	v_lshlrev_b32_e32 v88, 16, v102
	v_and_b32_e32 v89, 0xffff0000, v102
	v_lshlrev_b32_e32 v90, 16, v103
	v_and_b32_e32 v91, 0xffff0000, v103
	v_pk_add_f32 v[84:85], v[40:41], v[84:85]
	v_pk_add_f32 v[86:87], v[42:43], v[86:87]
	v_pk_add_f32 v[84:85], v[84:85], v[88:89]
	v_pk_add_f32 v[86:87], v[86:87], v[90:91]
	v_mul_f32_e32 v84, v82, v84
	v_mul_f32_e32 v85, v82, v85
	v_mul_f32_e32 v86, v82, v86
	v_mul_f32_e32 v87, v82, v87
	v_lshlrev_b32_e32 v88, 16, v196
	v_and_b32_e32 v89, 0xffff0000, v196
	v_lshlrev_b32_e32 v90, 16, v197
	v_and_b32_e32 v91, 0xffff0000, v197
	v_mul_f32_e32 v84, v84, v88
	v_mul_f32_e32 v85, v85, v89
	v_mul_f32_e32 v86, v86, v90
	v_mul_f32_e32 v87, v87, v91
	v_cvt_pk_bf16_f32 v84, v84, v85
	v_cvt_pk_bf16_f32 v85, v86, v87
	global_store_dwordx2 v66, v[84:85], s[20:21] offset:32
	s_waitcnt vmcnt(26)
; __device__ __forceinline__ unsigned cvt_pk_bf16(float lo, float hi) { unsigned r; asm volatile("v_cvt_pk_bf16_f32 %0, %1, %2" : "=v"(r) : "v"(lo), "v"(hi)); return r; }
; __device__ __forceinline__ float bflo(unsigned w) { return __uint_as_float(w << 16); }
; __device__ __forceinline__ float bfhi(unsigned w) { return __uint_as_float(w & 0xffff0000u); }
; template <bool DRY>
; __device__ __forceinline__ void attn_unit(const Args& a, LAS unsigned char* lds, int cidx, int h, int lane, int wave) {
;     ...
; #pragma unroll
;                 for (int c = 0; c < 8; ++c) {
;                     bf16_t* gp = (bf16_t*)((char*)GA + go) - 16 * c + 16 * c;
;                     const u32x2 xa = *(const u32x2*)((const char*)X + x1o + 32 * c), xb = *(const u32x2*)((const char*)X + x4o + 32 * c);
;                     const f32x4 t = o[gq][c] + (f32x4){bflo(xa.x), bfhi(xa.x), bflo(xa.y), bfhi(xa.y)} + (f32x4){bflo(xb.x), bfhi(xb.x), bflo(xb.y), bfhi(xb.y)};
;                     const u32x2 gg = *(const u32x2*)(gp + 16 * c);
;                     u32x2 w; w.x = cvt_pk_bf16(t[0] * inv * bflo(gg.x), t[1] * inv * bfhi(gg.x)); w.y = cvt_pk_bf16(t[2] * inv * bflo(gg.y), t[3] * inv * bfhi(gg.y));
;                     if (!DRY || inv == 1.2345e33f) *(u32x2*)(gp + 16 * c) = w;
;                 }
	v_lshlrev_b32_e32 v84, 16, v104
	v_and_b32_e32 v85, 0xffff0000, v104
	v_lshlrev_b32_e32 v86, 16, v105
	v_and_b32_e32 v87, 0xffff0000, v105
	v_lshlrev_b32_e32 v88, 16, v108
	v_and_b32_e32 v89, 0xffff0000, v108
	v_lshlrev_b32_e32 v90, 16, v109
	v_and_b32_e32 v91, 0xffff0000, v109
	v_pk_add_f32 v[84:85], v[56:57], v[84:85]
	v_pk_add_f32 v[86:87], v[58:59], v[86:87]
	v_pk_add_f32 v[84:85], v[84:85], v[88:89]
	v_pk_add_f32 v[86:87], v[86:87], v[90:91]
	v_mul_f32_e32 v84, v82, v84
	v_mul_f32_e32 v85, v82, v85
	v_mul_f32_e32 v86, v82, v86
	v_mul_f32_e32 v87, v82, v87
	v_lshlrev_b32_e32 v88, 16, v198
	v_and_b32_e32 v89, 0xffff0000, v198
	v_lshlrev_b32_e32 v90, 16, v199
	v_and_b32_e32 v91, 0xffff0000, v199
	v_mul_f32_e32 v84, v84, v88
	v_mul_f32_e32 v85, v85, v89
	v_mul_f32_e32 v86, v86, v90
	v_mul_f32_e32 v87, v87, v91
	v_cvt_pk_bf16_f32 v84, v84, v85
	v_cvt_pk_bf16_f32 v85, v86, v87
	global_store_dwordx2 v66, v[84:85], s[20:21] offset:64
	s_waitcnt vmcnt(27)
	v_lshlrev_b32_e32 v84, 16, v106
	v_and_b32_e32 v85, 0xffff0000, v106
	v_lshlrev_b32_e32 v86, 16, v107
	v_and_b32_e32 v87, 0xffff0000, v107
	v_lshlrev_b32_e32 v88, 16, v110
	v_and_b32_e32 v89, 0xffff0000, v110
	v_lshlrev_b32_e32 v90, 16, v111
	v_and_b32_e32 v91, 0xffff0000, v111
	v_pk_add_f32 v[84:85], v[52:53], v[84:85]
	v_pk_add_f32 v[86:87], v[54:55], v[86:87]
	v_pk_add_f32 v[84:85], v[84:85], v[88:89]
	v_pk_add_f32 v[86:87], v[86:87], v[90:91]
	v_mul_f32_e32 v84, v82, v84
	v_mul_f32_e32 v85, v82, v85
	v_mul_f32_e32 v86, v82, v86
	v_mul_f32_e32 v87, v82, v87
	v_lshlrev_b32_e32 v88, 16, v200
	v_and_b32_e32 v89, 0xffff0000, v200
	v_lshlrev_b32_e32 v90, 16, v201
	v_and_b32_e32 v91, 0xffff0000, v201
	v_mul_f32_e32 v84, v84, v88
	v_mul_f32_e32 v85, v85, v89
	v_mul_f32_e32 v86, v86, v90
	v_mul_f32_e32 v87, v87, v91
	v_cvt_pk_bf16_f32 v84, v84, v85
	v_cvt_pk_bf16_f32 v85, v86, v87
	global_store_dwordx2 v66, v[84:85], s[20:21] offset:96
	s_waitcnt vmcnt(24)
	v_lshlrev_b32_e32 v84, 16, v112
	v_and_b32_e32 v85, 0xffff0000, v112
	v_lshlrev_b32_e32 v86, 16, v113
	v_and_b32_e32 v87, 0xffff0000, v113
	v_lshlrev_b32_e32 v88, 16, v116
	v_and_b32_e32 v89, 0xffff0000, v116
	v_lshlrev_b32_e32 v90, 16, v117
	v_and_b32_e32 v91, 0xffff0000, v117
	v_pk_add_f32 v[84:85], v[48:49], v[84:85]
	v_pk_add_f32 v[86:87], v[50:51], v[86:87]
	v_pk_add_f32 v[84:85], v[84:85], v[88:89]
	v_pk_add_f32 v[86:87], v[86:87], v[90:91]
	v_mul_f32_e32 v84, v82, v84
	v_mul_f32_e32 v85, v82, v85
	v_mul_f32_e32 v86, v82, v86
	v_mul_f32_e32 v87, v82, v87
	v_lshlrev_b32_e32 v88, 16, v202
	v_and_b32_e32 v89, 0xffff0000, v202
	v_lshlrev_b32_e32 v90, 16, v203
	v_and_b32_e32 v91, 0xffff0000, v203
	v_mul_f32_e32 v84, v84, v88
	v_mul_f32_e32 v85, v85, v89
	v_mul_f32_e32 v86, v86, v90
	v_mul_f32_e32 v87, v87, v91
	v_cvt_pk_bf16_f32 v84, v84, v85
	v_cvt_pk_bf16_f32 v85, v86, v87
	global_store_dwordx2 v66, v[84:85], s[20:21] offset:128
	s_waitcnt vmcnt(25)
	v_lshlrev_b32_e32 v84, 16, v114
	v_and_b32_e32 v85, 0xffff0000, v114
	v_lshlrev_b32_e32 v86, 16, v115
	v_and_b32_e32 v87, 0xffff0000, v115
	v_lshlrev_b32_e32 v88, 16, v118
	v_and_b32_e32 v89, 0xffff0000, v118
	v_lshlrev_b32_e32 v90, 16, v119
	v_and_b32_e32 v91, 0xffff0000, v119
	v_pk_add_f32 v[84:85], v[44:45], v[84:85]
	v_pk_add_f32 v[86:87], v[46:47], v[86:87]
	v_pk_add_f32 v[84:85], v[84:85], v[88:89]
	v_pk_add_f32 v[86:87], v[86:87], v[90:91]
	v_mul_f32_e32 v84, v82, v84
	v_mul_f32_e32 v85, v82, v85
	v_mul_f32_e32 v86, v82, v86
	v_mul_f32_e32 v87, v82, v87
	v_lshlrev_b32_e32 v88, 16, v204
	v_and_b32_e32 v89, 0xffff0000, v204
	v_lshlrev_b32_e32 v90, 16, v205
	v_and_b32_e32 v91, 0xffff0000, v205
	v_mul_f32_e32 v84, v84, v88
	v_mul_f32_e32 v85, v85, v89
	v_mul_f32_e32 v86, v86, v90
	v_mul_f32_e32 v87, v87, v91
	v_cvt_pk_bf16_f32 v84, v84, v85
	v_cvt_pk_bf16_f32 v85, v86, v87
	global_store_dwordx2 v66, v[84:85], s[20:21] offset:160
	s_waitcnt vmcnt(22)
	v_lshlrev_b32_e32 v84, 16, v120
	v_and_b32_e32 v85, 0xffff0000, v120
	v_lshlrev_b32_e32 v86, 16, v121
	v_and_b32_e32 v87, 0xffff0000, v121
	v_lshlrev_b32_e32 v88, 16, v124
	v_and_b32_e32 v89, 0xffff0000, v124
	v_lshlrev_b32_e32 v90, 16, v125
	v_and_b32_e32 v91, 0xffff0000, v125
	v_pk_add_f32 v[84:85], v[36:37], v[84:85]
	v_pk_add_f32 v[86:87], v[38:39], v[86:87]
	v_pk_add_f32 v[84:85], v[84:85], v[88:89]
	v_pk_add_f32 v[86:87], v[86:87], v[90:91]
	v_mul_f32_e32 v84, v82, v84
	v_mul_f32_e32 v85, v82, v85
	v_mul_f32_e32 v86, v82, v86
	v_mul_f32_e32 v87, v82, v87
	v_lshlrev_b32_e32 v88, 16, v206
	v_and_b32_e32 v89, 0xffff0000, v206
	v_lshlrev_b32_e32 v90, 16, v207
	v_and_b32_e32 v91, 0xffff0000, v207
	v_mul_f32_e32 v84, v84, v88
	v_mul_f32_e32 v85, v85, v89
	v_mul_f32_e32 v86, v86, v90
	v_mul_f32_e32 v87, v87, v91
	v_cvt_pk_bf16_f32 v84, v84, v85
	v_cvt_pk_bf16_f32 v85, v86, v87
	global_store_dwordx2 v66, v[84:85], s[20:21] offset:192
	s_waitcnt vmcnt(23)
	v_lshlrev_b32_e32 v84, 16, v122
	v_and_b32_e32 v85, 0xffff0000, v122
	v_lshlrev_b32_e32 v86, 16, v123
	v_and_b32_e32 v87, 0xffff0000, v123
	v_lshlrev_b32_e32 v88, 16, v126
	v_and_b32_e32 v89, 0xffff0000, v126
	v_lshlrev_b32_e32 v90, 16, v127
	v_and_b32_e32 v91, 0xffff0000, v127
	v_pk_add_f32 v[84:85], v[32:33], v[84:85]
	v_pk_add_f32 v[86:87], v[34:35], v[86:87]
	v_pk_add_f32 v[84:85], v[84:85], v[88:89]
	v_pk_add_f32 v[86:87], v[86:87], v[90:91]
	v_mul_f32_e32 v84, v82, v84
	v_mul_f32_e32 v85, v82, v85
	v_mul_f32_e32 v86, v82, v86
	v_mul_f32_e32 v87, v82, v87
	v_lshlrev_b32_e32 v88, 16, v208
	v_and_b32_e32 v89, 0xffff0000, v208
	v_lshlrev_b32_e32 v90, 16, v209
	v_and_b32_e32 v91, 0xffff0000, v209
	v_mul_f32_e32 v84, v84, v88
	v_mul_f32_e32 v85, v85, v89
	v_mul_f32_e32 v86, v86, v90
	v_mul_f32_e32 v87, v87, v91
	v_cvt_pk_bf16_f32 v84, v84, v85
	v_cvt_pk_bf16_f32 v85, v86, v87
	global_store_dwordx2 v66, v[84:85], s[20:21] offset:224
	s_waitcnt vmcnt(20)
; __device__ __forceinline__ unsigned cvt_pk_bf16(float lo, float hi) { unsigned r; asm volatile("v_cvt_pk_bf16_f32 %0, %1, %2" : "=v"(r) : "v"(lo), "v"(hi)); return r; }
; __device__ __forceinline__ float bflo(unsigned w) { return __uint_as_float(w << 16); }
; __device__ __forceinline__ float bfhi(unsigned w) { return __uint_as_float(w & 0xffff0000u); }
; template <bool DRY>
; __device__ __forceinline__ void attn_unit(const Args& a, LAS unsigned char* lds, int cidx, int h, int lane, int wave) {
;     ...
; #pragma unroll
;                 for (int c = 0; c < 8; ++c) {
;                     bf16_t* gp = (bf16_t*)((char*)GA + go) - 16 * c + 16 * c;
;                     const u32x2 xa = *(const u32x2*)((const char*)X + x1o + 32 * c), xb = *(const u32x2*)((const char*)X + x4o + 32 * c);
;                     const f32x4 t = o[gq][c] + (f32x4){bflo(xa.x), bfhi(xa.x), bflo(xa.y), bfhi(xa.y)} + (f32x4){bflo(xb.x), bfhi(xb.x), bflo(xb.y), bfhi(xb.y)};
;                     const u32x2 gg = *(const u32x2*)(gp + 16 * c);
;                     u32x2 w; w.x = cvt_pk_bf16(t[0] * inv * bflo(gg.x), t[1] * inv * bfhi(gg.x)); w.y = cvt_pk_bf16(t[2] * inv * bflo(gg.y), t[3] * inv * bfhi(gg.y));
;                     if (!DRY || inv == 1.2345e33f) *(u32x2*)(gp + 16 * c) = w;
;                 }
	v_lshlrev_b32_e32 v84, 16, v128
	v_and_b32_e32 v85, 0xffff0000, v128
	v_lshlrev_b32_e32 v86, 16, v129
	v_and_b32_e32 v87, 0xffff0000, v129
	v_lshlrev_b32_e32 v88, 16, v132
	v_and_b32_e32 v89, 0xffff0000, v132
	v_lshlrev_b32_e32 v90, 16, v133
	v_and_b32_e32 v91, 0xffff0000, v133
	v_pk_add_f32 v[84:85], v[28:29], v[84:85]
	v_pk_add_f32 v[86:87], v[30:31], v[86:87]
	v_pk_add_f32 v[84:85], v[84:85], v[88:89]
	v_pk_add_f32 v[86:87], v[86:87], v[90:91]
	v_mul_f32_e32 v84, v83, v84
	v_mul_f32_e32 v85, v83, v85
	v_mul_f32_e32 v86, v83, v86
	v_mul_f32_e32 v87, v83, v87
	v_lshlrev_b32_e32 v88, 16, v210
	v_and_b32_e32 v89, 0xffff0000, v210
	v_lshlrev_b32_e32 v90, 16, v211
	v_and_b32_e32 v91, 0xffff0000, v211
	v_mul_f32_e32 v84, v84, v88
	v_mul_f32_e32 v85, v85, v89
	v_mul_f32_e32 v86, v86, v90
	v_mul_f32_e32 v87, v87, v91
	v_cvt_pk_bf16_f32 v84, v84, v85
	v_cvt_pk_bf16_f32 v85, v86, v87
	global_store_dwordx2 v67, v[84:85], s[20:21]
	s_waitcnt vmcnt(21)
	v_lshlrev_b32_e32 v84, 16, v130
	v_and_b32_e32 v85, 0xffff0000, v130
	v_lshlrev_b32_e32 v86, 16, v131
	v_and_b32_e32 v87, 0xffff0000, v131
	v_lshlrev_b32_e32 v88, 16, v134
	v_and_b32_e32 v89, 0xffff0000, v134
	v_lshlrev_b32_e32 v90, 16, v135
	v_and_b32_e32 v91, 0xffff0000, v135
	v_pk_add_f32 v[84:85], v[24:25], v[84:85]
	v_pk_add_f32 v[86:87], v[26:27], v[86:87]
	v_pk_add_f32 v[84:85], v[84:85], v[88:89]
	v_pk_add_f32 v[86:87], v[86:87], v[90:91]
	v_mul_f32_e32 v84, v83, v84
	v_mul_f32_e32 v85, v83, v85
	v_mul_f32_e32 v86, v83, v86
	v_mul_f32_e32 v87, v83, v87
	v_lshlrev_b32_e32 v88, 16, v212
	v_and_b32_e32 v89, 0xffff0000, v212
	v_lshlrev_b32_e32 v90, 16, v213
	v_and_b32_e32 v91, 0xffff0000, v213
	v_mul_f32_e32 v84, v84, v88
	v_mul_f32_e32 v85, v85, v89
	v_mul_f32_e32 v86, v86, v90
	v_mul_f32_e32 v87, v87, v91
	v_cvt_pk_bf16_f32 v84, v84, v85
	v_cvt_pk_bf16_f32 v85, v86, v87
	global_store_dwordx2 v67, v[84:85], s[20:21] offset:32
	s_waitcnt vmcnt(18)
	v_lshlrev_b32_e32 v84, 16, v136
	v_and_b32_e32 v85, 0xffff0000, v136
	v_lshlrev_b32_e32 v86, 16, v137
	v_and_b32_e32 v87, 0xffff0000, v137
	v_lshlrev_b32_e32 v88, 16, v140
	v_and_b32_e32 v89, 0xffff0000, v140
	v_lshlrev_b32_e32 v90, 16, v141
	v_and_b32_e32 v91, 0xffff0000, v141
	v_pk_add_f32 v[84:85], v[20:21], v[84:85]
	v_pk_add_f32 v[86:87], v[22:23], v[86:87]
	v_pk_add_f32 v[84:85], v[84:85], v[88:89]
	v_pk_add_f32 v[86:87], v[86:87], v[90:91]
	v_mul_f32_e32 v84, v83, v84
	v_mul_f32_e32 v85, v83, v85
	v_mul_f32_e32 v86, v83, v86
	v_mul_f32_e32 v87, v83, v87
	v_lshlrev_b32_e32 v88, 16, v214
	v_and_b32_e32 v89, 0xffff0000, v214
	v_lshlrev_b32_e32 v90, 16, v215
	v_and_b32_e32 v91, 0xffff0000, v215
	v_mul_f32_e32 v84, v84, v88
	v_mul_f32_e32 v85, v85, v89
	v_mul_f32_e32 v86, v86, v90
	v_mul_f32_e32 v87, v87, v91
	v_cvt_pk_bf16_f32 v84, v84, v85
	v_cvt_pk_bf16_f32 v85, v86, v87
	global_store_dwordx2 v67, v[84:85], s[20:21] offset:64
	s_waitcnt vmcnt(19)
	v_lshlrev_b32_e32 v84, 16, v138
	v_and_b32_e32 v85, 0xffff0000, v138
	v_lshlrev_b32_e32 v86, 16, v139
	v_and_b32_e32 v87, 0xffff0000, v139
	v_lshlrev_b32_e32 v88, 16, v142
	v_and_b32_e32 v89, 0xffff0000, v142
	v_lshlrev_b32_e32 v90, 16, v143
	v_and_b32_e32 v91, 0xffff0000, v143
	v_pk_add_f32 v[84:85], v[16:17], v[84:85]
	v_pk_add_f32 v[86:87], v[18:19], v[86:87]
	v_pk_add_f32 v[84:85], v[84:85], v[88:89]
	v_pk_add_f32 v[86:87], v[86:87], v[90:91]
	v_mul_f32_e32 v84, v83, v84
	v_mul_f32_e32 v85, v83, v85
	v_mul_f32_e32 v86, v83, v86
	v_mul_f32_e32 v87, v83, v87
	v_lshlrev_b32_e32 v88, 16, v216
	v_and_b32_e32 v89, 0xffff0000, v216
	v_lshlrev_b32_e32 v90, 16, v217
	v_and_b32_e32 v91, 0xffff0000, v217
	v_mul_f32_e32 v84, v84, v88
	v_mul_f32_e32 v85, v85, v89
	v_mul_f32_e32 v86, v86, v90
	v_mul_f32_e32 v87, v87, v91
	v_cvt_pk_bf16_f32 v84, v84, v85
	v_cvt_pk_bf16_f32 v85, v86, v87
	global_store_dwordx2 v67, v[84:85], s[20:21] offset:96
	s_waitcnt vmcnt(16)
	v_lshlrev_b32_e32 v84, 16, v144
	v_and_b32_e32 v85, 0xffff0000, v144
	v_lshlrev_b32_e32 v86, 16, v145
	v_and_b32_e32 v87, 0xffff0000, v145
	v_lshlrev_b32_e32 v88, 16, v148
	v_and_b32_e32 v89, 0xffff0000, v148
	v_lshlrev_b32_e32 v90, 16, v149
	v_and_b32_e32 v91, 0xffff0000, v149
	v_pk_add_f32 v[84:85], v[12:13], v[84:85]
	v_pk_add_f32 v[86:87], v[14:15], v[86:87]
	v_pk_add_f32 v[84:85], v[84:85], v[88:89]
	v_pk_add_f32 v[86:87], v[86:87], v[90:91]
	v_mul_f32_e32 v84, v83, v84
	v_mul_f32_e32 v85, v83, v85
	v_mul_f32_e32 v86, v83, v86
	v_mul_f32_e32 v87, v83, v87
	v_lshlrev_b32_e32 v88, 16, v218
	v_and_b32_e32 v89, 0xffff0000, v218
	v_lshlrev_b32_e32 v90, 16, v219
	v_and_b32_e32 v91, 0xffff0000, v219
	v_mul_f32_e32 v84, v84, v88
	v_mul_f32_e32 v85, v85, v89
	v_mul_f32_e32 v86, v86, v90
	v_mul_f32_e32 v87, v87, v91
	v_cvt_pk_bf16_f32 v84, v84, v85
	v_cvt_pk_bf16_f32 v85, v86, v87
	global_store_dwordx2 v67, v[84:85], s[20:21] offset:128
	s_waitcnt vmcnt(17)
; __device__ __forceinline__ unsigned cvt_pk_bf16(float lo, float hi) { unsigned r; asm volatile("v_cvt_pk_bf16_f32 %0, %1, %2" : "=v"(r) : "v"(lo), "v"(hi)); return r; }
; __device__ __forceinline__ float bflo(unsigned w) { return __uint_as_float(w << 16); }
; __device__ __forceinline__ float bfhi(unsigned w) { return __uint_as_float(w & 0xffff0000u); }
; template <bool DRY>
; __device__ __forceinline__ void attn_unit(const Args& a, LAS unsigned char* lds, int cidx, int h, int lane, int wave) {
;     ...
;             for (int gq = 0; gq < 2; ++gq) {
;                 const int qi = qpos[gq] - Pu;
;                 const unsigned xo = ((unsigned)(pi * 512 + qi) * 128 + 4 * fq) * 2u;
; #pragma unroll
;                 for (int c = 0; c < 8; ++c) { u32x2 w; w.x = cvt_pk_bf16(o[gq][c][0], o[gq][c][1]); w.y = cvt_pk_bf16(o[gq][c][2], o[gq][c][3]); *(u32x2*)((char*)X + xo + 32 * c) = w; }
;                 if (fq == 0) *(float*)((char*)Xd + (unsigned)(pi * 512 + qi) * 4u) = den[gq];
;     ...
;                 for (int c = 0; c < 8; ++c) {
;                     bf16_t* gp = (bf16_t*)((char*)GA + go) - 16 * c + 16 * c;
;                     const u32x2 xa = *(const u32x2*)((const char*)X + x1o + 32 * c), xb = *(const u32x2*)((const char*)X + x4o + 32 * c);
;                     const f32x4 t = o[gq][c] + (f32x4){bflo(xa.x), bfhi(xa.x), bflo(xa.y), bfhi(xa.y)} + (f32x4){bflo(xb.x), bfhi(xb.x), bflo(xb.y), bfhi(xb.y)};
;                     const u32x2 gg = *(const u32x2*)(gp + 16 * c);
;                     u32x2 w; w.x = cvt_pk_bf16(t[0] * inv * bflo(gg.x), t[1] * inv * bfhi(gg.x)); w.y = cvt_pk_bf16(t[2] * inv * bflo(gg.y), t[3] * inv * bfhi(gg.y));
;                     if (!DRY || inv == 1.2345e33f) *(u32x2*)(gp + 16 * c) = w;
;                 }
	v_lshlrev_b32_e32 v84, 16, v146
	v_and_b32_e32 v85, 0xffff0000, v146
	v_lshlrev_b32_e32 v86, 16, v147
	v_and_b32_e32 v87, 0xffff0000, v147
	v_lshlrev_b32_e32 v88, 16, v150
	v_and_b32_e32 v89, 0xffff0000, v150
	v_lshlrev_b32_e32 v90, 16, v151
	v_and_b32_e32 v91, 0xffff0000, v151
	v_pk_add_f32 v[84:85], v[8:9], v[84:85]
	v_pk_add_f32 v[86:87], v[10:11], v[86:87]
	v_pk_add_f32 v[84:85], v[84:85], v[88:89]
	v_pk_add_f32 v[86:87], v[86:87], v[90:91]
	v_mul_f32_e32 v84, v83, v84
	v_mul_f32_e32 v85, v83, v85
	v_mul_f32_e32 v86, v83, v86
	v_mul_f32_e32 v87, v83, v87
	v_lshlrev_b32_e32 v88, 16, v220
	v_and_b32_e32 v89, 0xffff0000, v220
	v_lshlrev_b32_e32 v90, 16, v221
	v_and_b32_e32 v91, 0xffff0000, v221
	v_mul_f32_e32 v84, v84, v88
	v_mul_f32_e32 v85, v85, v89
	v_mul_f32_e32 v86, v86, v90
	v_mul_f32_e32 v87, v87, v91
	v_cvt_pk_bf16_f32 v84, v84, v85
	v_cvt_pk_bf16_f32 v85, v86, v87
	global_store_dwordx2 v67, v[84:85], s[20:21] offset:160
	s_waitcnt vmcnt(14)
	v_lshlrev_b32_e32 v84, 16, v152
	v_and_b32_e32 v85, 0xffff0000, v152
	v_lshlrev_b32_e32 v86, 16, v153
	v_and_b32_e32 v87, 0xffff0000, v153
	v_lshlrev_b32_e32 v88, 16, v156
	v_and_b32_e32 v89, 0xffff0000, v156
	v_lshlrev_b32_e32 v90, 16, v157
	v_and_b32_e32 v91, 0xffff0000, v157
	v_pk_add_f32 v[84:85], v[4:5], v[84:85]
	v_pk_add_f32 v[86:87], v[6:7], v[86:87]
	v_pk_add_f32 v[84:85], v[84:85], v[88:89]
	v_pk_add_f32 v[86:87], v[86:87], v[90:91]
	v_mul_f32_e32 v84, v83, v84
	v_mul_f32_e32 v85, v83, v85
	v_mul_f32_e32 v86, v83, v86
	v_mul_f32_e32 v87, v83, v87
	v_lshlrev_b32_e32 v88, 16, v222
	v_and_b32_e32 v89, 0xffff0000, v222
	v_lshlrev_b32_e32 v90, 16, v223
	v_and_b32_e32 v91, 0xffff0000, v223
	v_mul_f32_e32 v84, v84, v88
	v_mul_f32_e32 v85, v85, v89
	v_mul_f32_e32 v86, v86, v90
	v_mul_f32_e32 v87, v87, v91
	v_cvt_pk_bf16_f32 v84, v84, v85
	v_cvt_pk_bf16_f32 v85, v86, v87
	global_store_dwordx2 v67, v[84:85], s[20:21] offset:192
	s_waitcnt vmcnt(15)
	v_lshlrev_b32_e32 v84, 16, v154
	v_and_b32_e32 v85, 0xffff0000, v154
	v_lshlrev_b32_e32 v86, 16, v155
	v_and_b32_e32 v87, 0xffff0000, v155
	v_lshlrev_b32_e32 v88, 16, v158
	v_and_b32_e32 v89, 0xffff0000, v158
	v_lshlrev_b32_e32 v90, 16, v159
	v_and_b32_e32 v91, 0xffff0000, v159
	v_pk_add_f32 v[84:85], v[0:1], v[84:85]
	v_pk_add_f32 v[86:87], v[2:3], v[86:87]
	v_pk_add_f32 v[84:85], v[84:85], v[88:89]
	v_pk_add_f32 v[86:87], v[86:87], v[90:91]
	v_mul_f32_e32 v84, v83, v84
	v_mul_f32_e32 v85, v83, v85
	v_mul_f32_e32 v86, v83, v86
	v_mul_f32_e32 v87, v83, v87
	v_lshlrev_b32_e32 v88, 16, v224
	v_and_b32_e32 v89, 0xffff0000, v224
	v_lshlrev_b32_e32 v90, 16, v225
	v_and_b32_e32 v91, 0xffff0000, v225
	v_mul_f32_e32 v84, v84, v88
	v_mul_f32_e32 v85, v85, v89
	v_mul_f32_e32 v86, v86, v90
	v_mul_f32_e32 v87, v87, v91
	v_cvt_pk_bf16_f32 v84, v84, v85
	v_cvt_pk_bf16_f32 v85, v86, v87
	global_store_dwordx2 v67, v[84:85], s[20:21] offset:224
	s_branch .LBB0_595
.LBB0_607:
	s_lshl_b32 s36, s52, 9
	v_subrev_u32_e32 v66, s50, v190
	v_add_u32_e32 v66, s36, v66
	s_and_b32 s37, s51, 1
	s_lshl_b32 s37, s37, 3
	s_add_i32 s37, s37, s78
	s_lshl_b32 s37, s37, 1
	s_lshl_b32 s98, s52, 5
	s_add_i32 s98, s98, s37
	s_lshl_b32 s98, s98, 12
	v_lshl_add_u32 v67, v162, 4, s98
	v_cvt_pk_bf16_f32 v60, v60, v61
	v_cvt_pk_bf16_f32 v61, v62, v63
	v_cvt_pk_bf16_f32 v62, v40, v41
	v_cvt_pk_bf16_f32 v63, v42, v43
	global_store_dwordx4 v67, v[60:63], s[22:23]
	v_cvt_pk_bf16_f32 v56, v56, v57
	v_cvt_pk_bf16_f32 v57, v58, v59
	v_cvt_pk_bf16_f32 v58, v52, v53
	v_cvt_pk_bf16_f32 v59, v54, v55
	global_store_dwordx4 v67, v[56:59], s[22:23] offset:1024
	v_cvt_pk_bf16_f32 v48, v48, v49
	v_cvt_pk_bf16_f32 v49, v50, v51
	v_cvt_pk_bf16_f32 v50, v44, v45
	v_cvt_pk_bf16_f32 v51, v46, v47
	global_store_dwordx4 v67, v[48:51], s[22:23] offset:2048
	v_cvt_pk_bf16_f32 v36, v36, v37
	v_cvt_pk_bf16_f32 v37, v38, v39
	v_cvt_pk_bf16_f32 v38, v32, v33
	v_cvt_pk_bf16_f32 v39, v34, v35
	global_store_dwordx4 v67, v[36:39], s[22:23] offset:3072
	s_and_saveexec_b64 s[6:7], s[4:5]
	s_cbranch_execz .LBB0_609
	v_lshlrev_b32_e32 v32, 2, v66
	global_store_dword v32, v65, s[30:31]
.LBB0_609:
	s_or_b64 exec, exec, s[6:7]
	v_subrev_u32_e32 v32, s50, v189
	v_add_u32_e32 v32, s36, v32
	v_add_u32_e32 v33, 0x1000, v67
	v_cvt_pk_bf16_f32 v28, v28, v29
	v_cvt_pk_bf16_f32 v29, v30, v31
	v_cvt_pk_bf16_f32 v30, v24, v25
	v_cvt_pk_bf16_f32 v31, v26, v27
	global_store_dwordx4 v33, v[28:31], s[22:23]
	v_cvt_pk_bf16_f32 v20, v20, v21
	v_cvt_pk_bf16_f32 v21, v22, v23
	v_cvt_pk_bf16_f32 v22, v16, v17
	v_cvt_pk_bf16_f32 v23, v18, v19
	global_store_dwordx4 v33, v[20:23], s[22:23] offset:1024
	v_cvt_pk_bf16_f32 v12, v12, v13
	v_cvt_pk_bf16_f32 v13, v14, v15
	v_cvt_pk_bf16_f32 v14, v8, v9
	v_cvt_pk_bf16_f32 v15, v10, v11
	global_store_dwordx4 v33, v[12:15], s[22:23] offset:2048
	v_cvt_pk_bf16_f32 v4, v4, v5
	v_cvt_pk_bf16_f32 v5, v6, v7
	v_cvt_pk_bf16_f32 v6, v0, v1
	v_cvt_pk_bf16_f32 v7, v2, v3
	global_store_dwordx4 v33, v[4:7], s[22:23] offset:3072
	s_and_saveexec_b64 s[6:7], s[4:5]
	s_cbranch_execz .LBB0_594
	v_lshlrev_b32_e32 v0, 2, v32
	global_store_dword v0, v64, s[30:31]
	s_branch .LBB0_594

; #define LAS __attribute__((address_space(3)))
; __global__ void __launch_bounds__(512, 2) fwd_kernel(Args args) {
;     extern __shared__ __attribute__((aligned(16))) unsigned char lds_raw[];
;     LAS unsigned char* lds = (LAS unsigned char*)lds_raw;
	.amdhsa_kernel _Z10fwd_kernel4Args
		.amdhsa_group_segment_fixed_size 0
		.amdhsa_private_segment_fixed_size 0
		.amdhsa_kernarg_size 432
		.amdhsa_user_sgpr_count 2
		.amdhsa_user_sgpr_dispatch_ptr 0
		.amdhsa_user_sgpr_queue_ptr 0
		.amdhsa_user_sgpr_kernarg_segment_ptr 1
		.amdhsa_user_sgpr_dispatch_id 0
		.amdhsa_user_sgpr_kernarg_preload_length 0
		.amdhsa_user_sgpr_kernarg_preload_offset 0
		.amdhsa_user_sgpr_private_segment_size 0
		.amdhsa_uses_dynamic_stack 0
		.amdhsa_enable_private_segment 0
		.amdhsa_system_sgpr_workgroup_id_x 1
		.amdhsa_system_sgpr_workgroup_id_y 0
		.amdhsa_system_sgpr_workgroup_id_z 0
		.amdhsa_system_sgpr_workgroup_info 0
		.amdhsa_system_vgpr_workitem_id 2
		.amdhsa_next_free_vgpr 256
		.amdhsa_next_free_sgpr 102
		.amdhsa_accum_offset 256
		.amdhsa_reserve_vcc 1
		.amdhsa_float_round_mode_32 0
		.amdhsa_float_round_mode_16_64 0
		.amdhsa_float_denorm_mode_32 3
		.amdhsa_float_denorm_mode_16_64 3
		.amdhsa_dx10_clamp 1
		.amdhsa_ieee_mode 1
		.amdhsa_fp16_overflow 0
		.amdhsa_tg_split 0
		.amdhsa_exception_fp_ieee_invalid_op 0
		.amdhsa_exception_fp_denorm_src 0
		.amdhsa_exception_fp_ieee_div_zero 0
		.amdhsa_exception_fp_ieee_overflow 0
		.amdhsa_exception_fp_ieee_underflow 0
		.amdhsa_exception_fp_ieee_inexact 0
		.amdhsa_exception_int_div_zero 0
	.end_amdhsa_kernel

amdhsa.kernels:
  - .agpr_count:     0
    .args:
      - .offset:         0
        .size:           176
        .value_kind:     by_value
      - .offset:         176
        .size:           4
        .value_kind:     hidden_block_count_x
      - .offset:         180
        .size:           4
        .value_kind:     hidden_block_count_y
      - .offset:         184
        .size:           4
        .value_kind:     hidden_block_count_z
      - .offset:         188
        .size:           2
        .value_kind:     hidden_group_size_x
      - .offset:         190
        .size:           2
        .value_kind:     hidden_group_size_y
      - .offset:         192
        .size:           2
        .value_kind:     hidden_group_size_z
      - .offset:         194
        .size:           2
        .value_kind:     hidden_remainder_x
      - .offset:         196
        .size:           2
        .value_kind:     hidden_remainder_y
      - .offset:         198
        .size:           2
        .value_kind:     hidden_remainder_z
      - .offset:         216
        .size:           8
        .value_kind:     hidden_global_offset_x
      - .offset:         224
        .size:           8
        .value_kind:     hidden_global_offset_y
      - .offset:         232
        .size:           8
        .value_kind:     hidden_global_offset_z
      - .offset:         240
        .size:           2
        .value_kind:     hidden_grid_dims
      - .offset:         264
        .size:           8
        .value_kind:     hidden_multigrid_sync_arg
      - .offset:         296
        .size:           4
        .value_kind:     hidden_dynamic_lds_size
    .group_segment_fixed_size: 0
    .kernarg_segment_align: 8
    .kernarg_segment_size: 432
    .language:       OpenCL C
    .language_version:
      - 2
      - 0
    .max_flat_workgroup_size: 512
    .name:           _Z10fwd_kernel4Args
    .private_segment_fixed_size: 0
    .sgpr_count:     108
    .sgpr_spill_count: 5
    .symbol:         _Z10fwd_kernel4Args.kd
    .uniform_work_group_size: 1
    .uses_dynamic_stack: false
    .vgpr_count:     256
    .vgpr_spill_count: 0
    .wavefront_size: 64
